# attention near-bias via ds_read2 immediate offsets (no per-element clamp except tile 4); mini_gemm loads hoisted
# speedup vs baseline: 1.0190x; 1.0040x over previous
.LBB0_268:
	s_andn2_b64 vcc, exec, s[0:1]
	s_cbranch_vccnz .LBB0_270
	s_cmp_lg_u32 s28, 4
	s_cbranch_scc1 .Latt_biasA_fast
	v_min_i32_e32 v32, 0x100, v247
	v_lshl_add_u32 v40, v32, 2, v246
	v_min_i32_e32 v32, 0x101, v247
	v_lshl_add_u32 v41, v32, 2, v246
	v_min_i32_e32 v32, 0x102, v247
	v_lshl_add_u32 v42, v32, 2, v246
	v_min_i32_e32 v32, 0x103, v247
	v_lshl_add_u32 v43, v32, 2, v246
	v_min_i32_e32 v32, 0x108, v247
	v_lshl_add_u32 v44, v32, 2, v246
	v_min_i32_e32 v32, 0x109, v247
	v_lshl_add_u32 v45, v32, 2, v246
	v_min_i32_e32 v32, 0x10a, v247
	v_lshl_add_u32 v46, v32, 2, v246
	v_min_i32_e32 v32, 0x10b, v247
	v_lshl_add_u32 v47, v32, 2, v246
	v_min_i32_e32 v32, 0x110, v247
	v_min_i32_e32 v33, 0x111, v247
	v_min_i32_e32 v34, 0x112, v247
	v_min_i32_e32 v35, 0x113, v247
	v_min_i32_e32 v36, 0x118, v247
	v_min_i32_e32 v37, 0x119, v247
	v_min_i32_e32 v38, 0x11a, v247
	v_min_i32_e32 v39, 0x11b, v247
	v_lshl_add_u32 v32, v32, 2, v246
	v_lshl_add_u32 v33, v33, 2, v246
	v_lshl_add_u32 v34, v34, 2, v246
	v_lshl_add_u32 v35, v35, 2, v246
	v_lshl_add_u32 v36, v36, 2, v246
	v_lshl_add_u32 v37, v37, 2, v246
	v_lshl_add_u32 v38, v38, 2, v246
	v_lshl_add_u32 v39, v39, 2, v246
	ds_read_b32 v32, v32 offset:188
	ds_read_b32 v33, v33 offset:184
	ds_read_b32 v34, v34 offset:180
	ds_read_b32 v35, v35 offset:176
	ds_read_b32 v36, v36 offset:156
	ds_read_b32 v37, v37 offset:152
	ds_read_b32 v38, v38 offset:148
	ds_read_b32 v39, v39 offset:144
	v_mov_b32_e32 v189, v238
	ds_read_b32 v238, v40 offset:252
	ds_read_b32 v239, v41 offset:248
	ds_read_b32 v240, v42 offset:244
	ds_read_b32 v241, v43 offset:240
	ds_read_b32 v242, v44 offset:220
	ds_read_b32 v243, v45 offset:216
	ds_read_b32 v234, v46 offset:212
	ds_read_b32 v235, v47 offset:208
	s_waitcnt lgkmcnt(10)
	v_pk_add_f32 v[44:45], v[60:61], v[36:37]
	v_pk_add_f32 v[42:43], v[58:59], v[34:35]
	s_waitcnt lgkmcnt(8)
	v_pk_add_f32 v[46:47], v[62:63], v[38:39]
	v_pk_add_f32 v[40:41], v[56:57], v[32:33]
	s_waitcnt lgkmcnt(0)
	v_pk_add_f32 v[38:39], v[54:55], v[234:235]
	v_pk_add_f32 v[36:37], v[52:53], v[242:243]
	v_pk_add_f32 v[34:35], v[50:51], v[240:241]
	v_pk_add_f32 v[32:33], v[48:49], v[238:239]
	v_mov_b32_e32 v238, v189

.LBB0_276:
	s_andn2_b64 vcc, exec, s[0:1]
	s_cbranch_vccnz .LBB0_278
	s_cmp_lg_u32 s28, 4
	s_cbranch_scc1 .Latt_biasB_fast
	v_subrev_u32_e32 v32, 32, v247
	v_min_i32_e32 v33, 0x100, v32
	v_lshl_add_u32 v40, v33, 2, v246
	v_min_i32_e32 v33, 0x101, v32
	v_lshl_add_u32 v41, v33, 2, v246
	v_min_i32_e32 v33, 0x102, v32
	v_lshl_add_u32 v42, v33, 2, v246
	v_min_i32_e32 v33, 0x103, v32
	v_lshl_add_u32 v43, v33, 2, v246
	v_min_i32_e32 v33, 0x108, v32
	v_lshl_add_u32 v44, v33, 2, v246
	v_min_i32_e32 v33, 0x109, v32
	v_lshl_add_u32 v45, v33, 2, v246
	v_min_i32_e32 v33, 0x10a, v32
	v_lshl_add_u32 v46, v33, 2, v246
	v_min_i32_e32 v33, 0x10b, v32
	v_lshl_add_u32 v47, v33, 2, v246
	v_min_i32_e32 v33, 0x110, v32
	v_min_i32_e32 v34, 0x111, v32
	v_min_i32_e32 v35, 0x112, v32
	v_min_i32_e32 v36, 0x113, v32
	v_min_i32_e32 v37, 0x118, v32
	v_min_i32_e32 v38, 0x119, v32
	v_min_i32_e32 v39, 0x11a, v32
	v_min_i32_e32 v32, 0x11b, v32
	v_lshl_add_u32 v33, v33, 2, v246
	v_lshl_add_u32 v34, v34, 2, v246
	v_lshl_add_u32 v35, v35, 2, v246
	v_lshl_add_u32 v36, v36, 2, v246
	v_lshl_add_u32 v37, v37, 2, v246
	v_lshl_add_u32 v38, v38, 2, v246
	v_lshl_add_u32 v39, v39, 2, v246
	v_lshl_add_u32 v216, v32, 2, v246
	ds_read_b32 v32, v33 offset:188
	ds_read_b32 v33, v34 offset:184
	ds_read_b32 v34, v35 offset:180
	ds_read_b32 v35, v36 offset:176
	ds_read_b32 v36, v37 offset:156
	ds_read_b32 v37, v38 offset:152
	ds_read_b32 v38, v39 offset:148
	ds_read_b32 v39, v216 offset:144
	ds_read_b32 v216, v40 offset:252
	ds_read_b32 v217, v41 offset:248
	ds_read_b32 v218, v42 offset:244
	ds_read_b32 v219, v43 offset:240
	ds_read_b32 v220, v44 offset:220
	ds_read_b32 v221, v45 offset:216
	ds_read_b32 v222, v46 offset:212
	ds_read_b32 v223, v47 offset:208
	s_waitcnt lgkmcnt(8)
	v_pk_add_f32 v[46:47], v[62:63], v[38:39]
	v_pk_add_f32 v[44:45], v[60:61], v[36:37]
	v_pk_add_f32 v[42:43], v[58:59], v[34:35]
	v_pk_add_f32 v[40:41], v[56:57], v[32:33]
	s_waitcnt lgkmcnt(0)
	v_pk_add_f32 v[38:39], v[54:55], v[222:223]
	v_pk_add_f32 v[36:37], v[52:53], v[220:221]
	v_pk_add_f32 v[34:35], v[50:51], v[218:219]
	v_pk_add_f32 v[32:33], v[48:49], v[216:217]

.Latt_biasA_fast:
	v_lshl_add_u32 v40, v247, 2, v246
	ds_read2_b32 v[38:39], v40 offset0:37 offset1:36
	ds_read2_b32 v[36:37], v40 offset0:39 offset1:38
	ds_read2_b32 v[34:35], v40 offset0:45 offset1:44
	ds_read2_b32 v[32:33], v40 offset0:47 offset1:46
	ds_read2_b32 v[222:223], v40 offset0:53 offset1:52
	ds_read2_b32 v[220:221], v40 offset0:55 offset1:54
	ds_read2_b32 v[218:219], v40 offset0:61 offset1:60
	ds_read2_b32 v[216:217], v40 offset0:63 offset1:62
	s_waitcnt lgkmcnt(4)
	v_pk_add_f32 v[46:47], v[62:63], v[38:39]
	v_pk_add_f32 v[44:45], v[60:61], v[36:37]
	v_pk_add_f32 v[42:43], v[58:59], v[34:35]
	v_pk_add_f32 v[40:41], v[56:57], v[32:33]
	s_waitcnt lgkmcnt(0)
	v_pk_add_f32 v[38:39], v[54:55], v[222:223]
	v_pk_add_f32 v[36:37], v[52:53], v[220:221]
	v_pk_add_f32 v[34:35], v[50:51], v[218:219]
	v_pk_add_f32 v[32:33], v[48:49], v[216:217]
	s_branch .LBB0_270
.Latt_biasB_fast:
	v_lshl_add_u32 v40, v247, 2, v246
	ds_read2_b32 v[38:39], v40 offset0:5 offset1:4
	ds_read2_b32 v[36:37], v40 offset0:7 offset1:6
	ds_read2_b32 v[34:35], v40 offset0:13 offset1:12
	ds_read2_b32 v[32:33], v40 offset0:15 offset1:14
	ds_read2_b32 v[222:223], v40 offset0:21 offset1:20
	ds_read2_b32 v[220:221], v40 offset0:23 offset1:22
	ds_read2_b32 v[218:219], v40 offset0:29 offset1:28
	ds_read2_b32 v[216:217], v40 offset0:31 offset1:30
	s_waitcnt lgkmcnt(4)
	v_pk_add_f32 v[46:47], v[62:63], v[38:39]
	v_pk_add_f32 v[44:45], v[60:61], v[36:37]
	v_pk_add_f32 v[42:43], v[58:59], v[34:35]
	v_pk_add_f32 v[40:41], v[56:57], v[32:33]
	s_waitcnt lgkmcnt(0)
	v_pk_add_f32 v[38:39], v[54:55], v[222:223]
	v_pk_add_f32 v[36:37], v[52:53], v[220:221]
	v_pk_add_f32 v[34:35], v[50:51], v[218:219]
	v_pk_add_f32 v[32:33], v[48:49], v[216:217]
	s_branch .LBB0_278

.LBB0_661:
	s_ashr_i32 s6, s4, 1
	s_and_b32 s6, s6, -16
	v_or_b32_e32 v0, s6, v8
	s_lshl_b32 s7, s4, 5
	v_mad_i64_i32 v[0:1], s[8:9], v0, s12, 0
	s_and_b32 s7, s7, 0x3e0
	v_lshl_add_u64 v[18:19], v[0:1], 1, v[10:11]
	v_or_b32_e32 v0, s7, v8
	v_mul_u32_u24_e32 v0, s12, v0
	v_lshlrev_b32_e32 v112, 1, v0
	v_mov_b32_e32 v0, 0
	v_lshl_add_u64 v[20:21], v[12:13], 0, v[112:113]
	s_mov_b32 s8, s5
	v_mov_b32_e32 v1, v0
	v_mov_b32_e32 v2, v0
	v_mov_b32_e32 v3, v0
	v_mov_b32_e32 v4, v0
	v_mov_b32_e32 v5, v0
	v_mov_b32_e32 v6, v0
	v_mov_b32_e32 v7, v0
	s_cmp_eq_u32 s5, 4
	s_cbranch_scc0 .Lmg_not4
	v_lshl_add_u64 v[32:33], v[20:21], 0, s[2:3]
	global_load_dwordx4 v[40:43], v[18:19], off
	global_load_dwordx4 v[44:47], v[20:21], off
	global_load_dwordx4 v[48:51], v[32:33], off
	global_load_dwordx4 v[52:55], v[18:19], off offset:64
	global_load_dwordx4 v[56:59], v[20:21], off offset:64
	global_load_dwordx4 v[60:63], v[32:33], off offset:64
	global_load_dwordx4 v[64:67], v[18:19], off offset:128
	global_load_dwordx4 v[68:71], v[20:21], off offset:128
	global_load_dwordx4 v[72:75], v[32:33], off offset:128
	global_load_dwordx4 v[76:79], v[18:19], off offset:192
	global_load_dwordx4 v[80:83], v[20:21], off offset:192
	global_load_dwordx4 v[84:87], v[32:33], off offset:192
	s_waitcnt vmcnt(9)
	v_mfma_f32_16x16x32_bf16 v[0:3], v[40:43], v[44:47], v[0:3]
	v_mfma_f32_16x16x32_bf16 v[4:7], v[40:43], v[48:51], v[4:7]
	s_waitcnt vmcnt(6)
	v_mfma_f32_16x16x32_bf16 v[0:3], v[52:55], v[56:59], v[0:3]
	v_mfma_f32_16x16x32_bf16 v[4:7], v[52:55], v[60:63], v[4:7]
	s_waitcnt vmcnt(3)
	v_mfma_f32_16x16x32_bf16 v[0:3], v[64:67], v[68:71], v[0:3]
	v_mfma_f32_16x16x32_bf16 v[4:7], v[64:67], v[72:75], v[4:7]
	s_waitcnt vmcnt(0)
	v_mfma_f32_16x16x32_bf16 v[0:3], v[76:79], v[80:83], v[0:3]
	v_mfma_f32_16x16x32_bf16 v[4:7], v[76:79], v[84:87], v[4:7]
	s_nop 7
	s_branch .Lmg_done
.Lmg_not4:
	s_cmp_eq_u32 s5, 11
	s_cbranch_scc0 .LBB0_662
	v_lshl_add_u64 v[32:33], v[20:21], 0, s[2:3]
	global_load_dwordx4 v[40:43], v[18:19], off
	global_load_dwordx4 v[44:47], v[20:21], off
	global_load_dwordx4 v[48:51], v[32:33], off
	global_load_dwordx4 v[52:55], v[18:19], off offset:64
	global_load_dwordx4 v[56:59], v[20:21], off offset:64
	global_load_dwordx4 v[60:63], v[32:33], off offset:64
	global_load_dwordx4 v[64:67], v[18:19], off offset:128
	global_load_dwordx4 v[68:71], v[20:21], off offset:128
	global_load_dwordx4 v[72:75], v[32:33], off offset:128
	global_load_dwordx4 v[76:79], v[18:19], off offset:192
	global_load_dwordx4 v[80:83], v[20:21], off offset:192
	global_load_dwordx4 v[84:87], v[32:33], off offset:192
	global_load_dwordx4 v[88:91], v[18:19], off offset:256
	global_load_dwordx4 v[92:95], v[20:21], off offset:256
	global_load_dwordx4 v[96:99], v[32:33], off offset:256
	global_load_dwordx4 v[100:103], v[18:19], off offset:320
	global_load_dwordx4 v[104:107], v[20:21], off offset:320
	global_load_dwordx4 v[108:111], v[32:33], off offset:320
	global_load_dwordx4 v[114:117], v[18:19], off offset:384
	global_load_dwordx4 v[118:121], v[20:21], off offset:384
	global_load_dwordx4 v[122:125], v[32:33], off offset:384
	global_load_dwordx4 v[126:129], v[18:19], off offset:448
	global_load_dwordx4 v[130:133], v[20:21], off offset:448
	global_load_dwordx4 v[134:137], v[32:33], off offset:448
	global_load_dwordx4 v[138:141], v[18:19], off offset:512
	global_load_dwordx4 v[142:145], v[20:21], off offset:512
	global_load_dwordx4 v[146:149], v[32:33], off offset:512
	global_load_dwordx4 v[150:153], v[18:19], off offset:576
	global_load_dwordx4 v[154:157], v[20:21], off offset:576
	global_load_dwordx4 v[158:161], v[32:33], off offset:576
	global_load_dwordx4 v[162:165], v[18:19], off offset:640
	global_load_dwordx4 v[166:169], v[20:21], off offset:640
	global_load_dwordx4 v[170:173], v[32:33], off offset:640
	s_waitcnt vmcnt(30)
	v_mfma_f32_16x16x32_bf16 v[0:3], v[40:43], v[44:47], v[0:3]
	v_mfma_f32_16x16x32_bf16 v[4:7], v[40:43], v[48:51], v[4:7]
	s_waitcnt vmcnt(27)
	v_mfma_f32_16x16x32_bf16 v[0:3], v[52:55], v[56:59], v[0:3]
	v_mfma_f32_16x16x32_bf16 v[4:7], v[52:55], v[60:63], v[4:7]
	s_waitcnt vmcnt(24)
	v_mfma_f32_16x16x32_bf16 v[0:3], v[64:67], v[68:71], v[0:3]
	v_mfma_f32_16x16x32_bf16 v[4:7], v[64:67], v[72:75], v[4:7]
	s_waitcnt vmcnt(21)
	v_mfma_f32_16x16x32_bf16 v[0:3], v[76:79], v[80:83], v[0:3]
	v_mfma_f32_16x16x32_bf16 v[4:7], v[76:79], v[84:87], v[4:7]
	s_waitcnt vmcnt(18)
	v_mfma_f32_16x16x32_bf16 v[0:3], v[88:91], v[92:95], v[0:3]
	v_mfma_f32_16x16x32_bf16 v[4:7], v[88:91], v[96:99], v[4:7]
	s_waitcnt vmcnt(15)
	v_mfma_f32_16x16x32_bf16 v[0:3], v[100:103], v[104:107], v[0:3]
	v_mfma_f32_16x16x32_bf16 v[4:7], v[100:103], v[108:111], v[4:7]
	s_waitcnt vmcnt(12)
	v_mfma_f32_16x16x32_bf16 v[0:3], v[114:117], v[118:121], v[0:3]
	v_mfma_f32_16x16x32_bf16 v[4:7], v[114:117], v[122:125], v[4:7]
	s_waitcnt vmcnt(9)
	v_mfma_f32_16x16x32_bf16 v[0:3], v[126:129], v[130:133], v[0:3]
	v_mfma_f32_16x16x32_bf16 v[4:7], v[126:129], v[134:137], v[4:7]
	s_waitcnt vmcnt(6)
	v_mfma_f32_16x16x32_bf16 v[0:3], v[138:141], v[142:145], v[0:3]
	v_mfma_f32_16x16x32_bf16 v[4:7], v[138:141], v[146:149], v[4:7]
	s_waitcnt vmcnt(3)
	v_mfma_f32_16x16x32_bf16 v[0:3], v[150:153], v[154:157], v[0:3]
	v_mfma_f32_16x16x32_bf16 v[4:7], v[150:153], v[158:161], v[4:7]
	s_waitcnt vmcnt(0)
	v_mfma_f32_16x16x32_bf16 v[0:3], v[162:165], v[166:169], v[0:3]
	v_mfma_f32_16x16x32_bf16 v[4:7], v[162:165], v[170:173], v[4:7]
	s_nop 7
	s_branch .Lmg_done

.Lmg_done:
	s_nop 3
	ds_write2st64_b32 v23, v0, v1 offset1:1
	s_nop 1
	ds_write2st64_b32 v23, v4, v5 offset0:4 offset1:5
	ds_write2st64_b32 v23, v2, v3 offset0:2 offset1:3
	ds_write2st64_b32 v23, v6, v7 offset0:6 offset1:7
	s_waitcnt lgkmcnt(0)
	s_barrier
	ds_read2st64_b32 v[0:1], v9 offset1:8
	ds_read2st64_b32 v[2:3], v9 offset0:16 offset1:24
	ds_read2st64_b32 v[4:5], v9 offset0:32 offset1:40
	s_lshl_b32 s66, s7, 1
	v_mov_b32_e32 v17, v113
	s_waitcnt lgkmcnt(2)
	v_add_f32_e32 v0, 0, v0
	v_add_f32_e32 v6, v0, v1
	ds_read2st64_b32 v[0:1], v9 offset0:48 offset1:56
	s_waitcnt lgkmcnt(2)
	v_add_f32_e32 v2, v6, v2
	v_add_f32_e32 v2, v2, v3
	s_waitcnt lgkmcnt(1)
	v_add_f32_e32 v2, v2, v4
	v_add_f32_e32 v2, v2, v5
	s_waitcnt lgkmcnt(0)
	v_add_f32_e32 v0, v2, v0
	v_add_f32_e32 v0, v0, v1
	v_cvt_pk_bf16_f32 v2, v0, s0
	v_or_b32_e32 v0, s6, v22
	v_ashrrev_i32_e32 v1, 31, v0
	v_lshlrev_b64 v[0:1], 11, v[0:1]
	v_lshl_add_u64 v[0:1], s[0:1], 0, v[0:1]
	v_lshl_add_u64 v[0:1], v[0:1], 0, s[66:67]
	v_lshl_add_u64 v[0:1], v[14:15], 1, v[0:1]
	v_lshl_add_u64 v[0:1], v[0:1], 0, v[16:17]
	s_mov_b32 s6, s54
	global_store_short v[0:1], v2, off
	s_barrier
	s_add_i32 s4, s6, s4
	s_cmpk_gt_i32 s4, 0xff
	s_cbranch_scc0 .LBB0_661
